# baseline (speedup 1.0000x reference)
; __device__ __forceinline__ float bf_lo(u32 v) { return __uint_as_float(v << 16); }
; __device__ __forceinline__ float bf_hi(u32 v) { return __uint_as_float(v & 0xffff0000u); }
; __device__ __forceinline__ void gemm_tile(const TileDesc& td, char* shm_c, const int wv) {
;     ...
;   } else {
;     #pragma unroll
;     for (int ai = 0; ai < 2; ++ai)
;     #pragma unroll
;     for (int m = 0; m < 4; ++m) {
;       int f0 = td.brow + ai * 128 + m * 16 + ar_l;
;       float4 ps = *(const float4*)(td.aux + f0);
;       #pragma unroll
;       for (int bj = 0; bj < 2; ++bj)
;       #pragma unroll
;       for (int n = 0; n < 2; ++n) {
;         long o = (long)(td.bcol + bj * 128 + n * 16 + br_l) * td.ldo + f0;
;         uint2 g = *(const uint2*)(td.outb + o);
;         f32x4 v = acc[ai][bj][m][n];
;         uint2 pk;
;         pk.x = pack2(v[0] * ps.x * bf_lo(g.x), v[1] * ps.y * bf_hi(g.x));
;         pk.y = pack2(v[2] * ps.z * bf_lo(g.y), v[3] * ps.w * bf_hi(g.y));
;         *(uint2*)(td.outb + o) = pk;
;       }
;     }
.LBB0_482:
	s_lshl_b64 s[28:29], s[28:29], 2
	v_mbcnt_lo_u32_b32 v128, -1, 0
	v_mbcnt_hi_u32_b32 v128, -1, v128
	s_add_u32 s28, s80, s28
	v_lshrrev_b32_e32 v130, 2, v128
	v_and_or_b32 v130, v130, 12, s40
	v_and_or_b32 v131, v128, 15, s44
	s_addc_u32 s29, s81, s29
	v_lshl_add_u32 v128, s63, 8, v130
	v_lshl_or_b32 v130, s62, 7, v131
	s_add_u32 s26, s38, s26
	v_mul_u32_u24_e32 v130, 0x2800, v130
	s_addc_u32 s27, s39, s27
	v_lshlrev_b32_e32 v130, 1, v130
	v_mov_b32_e32 v131, v129
	v_lshl_add_u64 v[132:133], v[128:129], 2, s[28:29]
	v_lshl_add_u64 v[136:137], s[26:27], 0, v[130:131]
	v_lshlrev_b32_e32 v128, 1, v128
	s_mov_b64 s[26:27], 0x50000
	v_lshl_add_u64 v[130:131], v[136:137], 0, v[128:129]
	v_lshl_add_u64 v[138:139], v[136:137], 0, s[26:27]
	s_mov_b64 s[26:27], 0x280000
	v_mbcnt_lo_u32_b32 v246, -1, 0
	v_mbcnt_hi_u32_b32 v246, -1, v246
	v_and_b32_e32 v244, 16, v246
	v_lshrrev_b32_e32 v245, 1, v244
	v_add_u32_e32 v244, v244, v245
	v_mov_b32_e32 v245, 0
	v_lshl_add_u64 v[130:131], v[130:131], 0, v[244:245]
	v_add_co_u32_e32 v134, vcc, 0x50000, v130
	s_nop 1
	v_addc_co_u32_e32 v135, vcc, 0, v131, vcc
	v_add_co_u32_e32 v136, vcc, 0x280000, v130
	s_nop 1
	v_addc_co_u32_e32 v137, vcc, 0, v131, vcc
	v_add_co_u32_e32 v138, vcc, 0x2d0000, v130
	s_nop 1
	v_addc_co_u32_e32 v139, vcc, 0, v131, vcc
	s_mov_b64 s[26:27], 0x2d0000
	global_load_dwordx4 v[144:147], v[132:133], off
	global_load_dwordx4 v[148:151], v[132:133], off offset:64
	global_load_dwordx4 v[152:155], v[132:133], off offset:128
	global_load_dwordx4 v[156:159], v[132:133], off offset:192
	global_load_dwordx4 v[160:163], v[132:133], off offset:512
	global_load_dwordx4 v[164:167], v[132:133], off offset:576
	global_load_dwordx4 v[168:171], v[132:133], off offset:640
	global_load_dwordx4 v[172:175], v[132:133], off offset:704
	global_load_dwordx4 v[176:179], v[130:131], off
	global_load_dwordx4 v[180:183], v[134:135], off
	global_load_dwordx4 v[184:187], v[136:137], off
	global_load_dwordx4 v[188:191], v[138:139], off
	global_load_dwordx4 v[192:195], v[130:131], off offset:64
	global_load_dwordx4 v[196:199], v[134:135], off offset:64
	global_load_dwordx4 v[200:203], v[136:137], off offset:64
	global_load_dwordx4 v[204:207], v[138:139], off offset:64
	global_load_dwordx4 v[208:211], v[130:131], off offset:256
	global_load_dwordx4 v[212:215], v[134:135], off offset:256
	global_load_dwordx4 v[216:219], v[136:137], off offset:256
	global_load_dwordx4 v[220:223], v[138:139], off offset:256
	global_load_dwordx4 v[224:227], v[130:131], off offset:320
	global_load_dwordx4 v[228:231], v[134:135], off offset:320
	global_load_dwordx4 v[232:235], v[136:137], off offset:320
	global_load_dwordx4 v[236:239], v[138:139], off offset:320
	s_add_i32 s61, s61, s91
	s_add_i32 s53, s53, s54
	s_cmpk_lt_i32 s61, 0x200
	v_readlane_b32 s67, v255, 34
	s_waitcnt vmcnt(15)
	v_permlane16_swap_b32_e32 v176, v178
	v_permlane16_swap_b32_e32 v177, v179
	v_pk_mul_f32 v[112:113], v[112:113], v[144:145]
	v_pk_mul_f32 v[114:115], v[114:115], v[146:147]
	v_pk_mul_f32 v[108:109], v[108:109], v[148:149]
	v_pk_mul_f32 v[110:111], v[110:111], v[150:151]
	v_lshlrev_b32_e32 v240, 16, v176
	v_and_b32_e32 v241, 0xffff0000, v176
	v_lshlrev_b32_e32 v242, 16, v177
	v_and_b32_e32 v243, 0xffff0000, v177
	v_pk_mul_f32 v[112:113], v[112:113], v[240:241]
	v_pk_mul_f32 v[114:115], v[114:115], v[242:243]
	v_lshlrev_b32_e32 v240, 16, v178
	v_and_b32_e32 v241, 0xffff0000, v178
	v_lshlrev_b32_e32 v242, 16, v179
	v_and_b32_e32 v243, 0xffff0000, v179
	v_pk_mul_f32 v[108:109], v[108:109], v[240:241]
	v_pk_mul_f32 v[110:111], v[110:111], v[242:243]
	v_cvt_pk_bf16_f32 v112, v112, v113
	v_cvt_pk_bf16_f32 v113, v114, v115
	v_cvt_pk_bf16_f32 v114, v108, v109
	v_cvt_pk_bf16_f32 v115, v110, v111
	s_nop 1
	v_permlane16_swap_b32_e32 v112, v114
	v_permlane16_swap_b32_e32 v113, v115
	global_store_dwordx4 v[130:131], v[112:115], off
	s_waitcnt vmcnt(15)
	v_permlane16_swap_b32_e32 v180, v182
	v_permlane16_swap_b32_e32 v181, v183
	v_pk_mul_f32 v[116:117], v[116:117], v[144:145]
	v_pk_mul_f32 v[118:119], v[118:119], v[146:147]
	v_pk_mul_f32 v[96:97], v[96:97], v[148:149]
	v_pk_mul_f32 v[98:99], v[98:99], v[150:151]
	v_lshlrev_b32_e32 v240, 16, v180
	v_and_b32_e32 v241, 0xffff0000, v180
	v_lshlrev_b32_e32 v242, 16, v181
	v_and_b32_e32 v243, 0xffff0000, v181
	v_pk_mul_f32 v[116:117], v[116:117], v[240:241]
	v_pk_mul_f32 v[118:119], v[118:119], v[242:243]
	v_lshlrev_b32_e32 v240, 16, v182
	v_and_b32_e32 v241, 0xffff0000, v182
	v_lshlrev_b32_e32 v242, 16, v183
	v_and_b32_e32 v243, 0xffff0000, v183
	v_pk_mul_f32 v[96:97], v[96:97], v[240:241]
	v_pk_mul_f32 v[98:99], v[98:99], v[242:243]
	v_cvt_pk_bf16_f32 v116, v116, v117
	v_cvt_pk_bf16_f32 v117, v118, v119
	v_cvt_pk_bf16_f32 v118, v96, v97
	v_cvt_pk_bf16_f32 v119, v98, v99
	s_nop 1
	v_permlane16_swap_b32_e32 v116, v118
	v_permlane16_swap_b32_e32 v117, v119
	global_store_dwordx4 v[134:135], v[116:119], off
	s_waitcnt vmcnt(15)
	v_permlane16_swap_b32_e32 v184, v186
	v_permlane16_swap_b32_e32 v185, v187
	v_pk_mul_f32 v[120:121], v[120:121], v[144:145]
	v_pk_mul_f32 v[122:123], v[122:123], v[146:147]
	v_pk_mul_f32 v[104:105], v[104:105], v[148:149]
	v_pk_mul_f32 v[106:107], v[106:107], v[150:151]
	v_lshlrev_b32_e32 v240, 16, v184
	v_and_b32_e32 v241, 0xffff0000, v184
	v_lshlrev_b32_e32 v242, 16, v185
	v_and_b32_e32 v243, 0xffff0000, v185
	v_pk_mul_f32 v[120:121], v[120:121], v[240:241]
	v_pk_mul_f32 v[122:123], v[122:123], v[242:243]
	v_lshlrev_b32_e32 v240, 16, v186
	v_and_b32_e32 v241, 0xffff0000, v186
	v_lshlrev_b32_e32 v242, 16, v187
	v_and_b32_e32 v243, 0xffff0000, v187
	v_pk_mul_f32 v[104:105], v[104:105], v[240:241]
	v_pk_mul_f32 v[106:107], v[106:107], v[242:243]
	v_cvt_pk_bf16_f32 v120, v120, v121
	v_cvt_pk_bf16_f32 v121, v122, v123
	v_cvt_pk_bf16_f32 v122, v104, v105
	v_cvt_pk_bf16_f32 v123, v106, v107
	s_nop 1
	v_permlane16_swap_b32_e32 v120, v122
	v_permlane16_swap_b32_e32 v121, v123
	global_store_dwordx4 v[136:137], v[120:123], off
	s_waitcnt vmcnt(15)
; __device__ __forceinline__ float bf_lo(u32 v) { return __uint_as_float(v << 16); }
; __device__ __forceinline__ float bf_hi(u32 v) { return __uint_as_float(v & 0xffff0000u); }
; __device__ __forceinline__ void gemm_tile(const TileDesc& td, char* shm_c, const int wv) {
;     ...
;   } else {
;     #pragma unroll
;     for (int ai = 0; ai < 2; ++ai)
;     #pragma unroll
;     for (int m = 0; m < 4; ++m) {
;       int f0 = td.brow + ai * 128 + m * 16 + ar_l;
;       float4 ps = *(const float4*)(td.aux + f0);
;       #pragma unroll
;       for (int bj = 0; bj < 2; ++bj)
;       #pragma unroll
;       for (int n = 0; n < 2; ++n) {
;         long o = (long)(td.bcol + bj * 128 + n * 16 + br_l) * td.ldo + f0;
;         uint2 g = *(const uint2*)(td.outb + o);
;         f32x4 v = acc[ai][bj][m][n];
;         uint2 pk;
;         pk.x = pack2(v[0] * ps.x * bf_lo(g.x), v[1] * ps.y * bf_hi(g.x));
;         pk.y = pack2(v[2] * ps.z * bf_lo(g.y), v[3] * ps.w * bf_hi(g.y));
;         *(uint2*)(td.outb + o) = pk;
;       }
;     }
	v_permlane16_swap_b32_e32 v188, v190
	v_permlane16_swap_b32_e32 v189, v191
	v_pk_mul_f32 v[124:125], v[124:125], v[144:145]
	v_pk_mul_f32 v[126:127], v[126:127], v[146:147]
	v_pk_mul_f32 v[100:101], v[100:101], v[148:149]
	v_pk_mul_f32 v[102:103], v[102:103], v[150:151]
	v_lshlrev_b32_e32 v240, 16, v188
	v_and_b32_e32 v241, 0xffff0000, v188
	v_lshlrev_b32_e32 v242, 16, v189
	v_and_b32_e32 v243, 0xffff0000, v189
	v_pk_mul_f32 v[124:125], v[124:125], v[240:241]
	v_pk_mul_f32 v[126:127], v[126:127], v[242:243]
	v_lshlrev_b32_e32 v240, 16, v190
	v_and_b32_e32 v241, 0xffff0000, v190
	v_lshlrev_b32_e32 v242, 16, v191
	v_and_b32_e32 v243, 0xffff0000, v191
	v_pk_mul_f32 v[100:101], v[100:101], v[240:241]
	v_pk_mul_f32 v[102:103], v[102:103], v[242:243]
	v_cvt_pk_bf16_f32 v124, v124, v125
	v_cvt_pk_bf16_f32 v125, v126, v127
	v_cvt_pk_bf16_f32 v126, v100, v101
	v_cvt_pk_bf16_f32 v127, v102, v103
	s_nop 1
	v_permlane16_swap_b32_e32 v124, v126
	v_permlane16_swap_b32_e32 v125, v127
	global_store_dwordx4 v[138:139], v[124:127], off
	s_waitcnt vmcnt(15)
	v_permlane16_swap_b32_e32 v192, v194
	v_permlane16_swap_b32_e32 v193, v195
	v_pk_mul_f32 v[92:93], v[92:93], v[152:153]
	v_pk_mul_f32 v[94:95], v[94:95], v[154:155]
	v_pk_mul_f32 v[76:77], v[76:77], v[156:157]
	v_pk_mul_f32 v[78:79], v[78:79], v[158:159]
	v_lshlrev_b32_e32 v240, 16, v192
	v_and_b32_e32 v241, 0xffff0000, v192
	v_lshlrev_b32_e32 v242, 16, v193
	v_and_b32_e32 v243, 0xffff0000, v193
	v_pk_mul_f32 v[92:93], v[92:93], v[240:241]
	v_pk_mul_f32 v[94:95], v[94:95], v[242:243]
	v_lshlrev_b32_e32 v240, 16, v194
	v_and_b32_e32 v241, 0xffff0000, v194
	v_lshlrev_b32_e32 v242, 16, v195
	v_and_b32_e32 v243, 0xffff0000, v195
	v_pk_mul_f32 v[76:77], v[76:77], v[240:241]
	v_pk_mul_f32 v[78:79], v[78:79], v[242:243]
	v_cvt_pk_bf16_f32 v92, v92, v93
	v_cvt_pk_bf16_f32 v93, v94, v95
	v_cvt_pk_bf16_f32 v94, v76, v77
	v_cvt_pk_bf16_f32 v95, v78, v79
	s_nop 1
	v_permlane16_swap_b32_e32 v92, v94
	v_permlane16_swap_b32_e32 v93, v95
	global_store_dwordx4 v[130:131], v[92:95], off offset:64
	s_waitcnt vmcnt(15)
	v_permlane16_swap_b32_e32 v196, v198
	v_permlane16_swap_b32_e32 v197, v199
	v_pk_mul_f32 v[80:81], v[80:81], v[152:153]
	v_pk_mul_f32 v[82:83], v[82:83], v[154:155]
	v_pk_mul_f32 v[64:65], v[64:65], v[156:157]
	v_pk_mul_f32 v[66:67], v[66:67], v[158:159]
	v_lshlrev_b32_e32 v240, 16, v196
	v_and_b32_e32 v241, 0xffff0000, v196
	v_lshlrev_b32_e32 v242, 16, v197
	v_and_b32_e32 v243, 0xffff0000, v197
	v_pk_mul_f32 v[80:81], v[80:81], v[240:241]
	v_pk_mul_f32 v[82:83], v[82:83], v[242:243]
	v_lshlrev_b32_e32 v240, 16, v198
	v_and_b32_e32 v241, 0xffff0000, v198
	v_lshlrev_b32_e32 v242, 16, v199
	v_and_b32_e32 v243, 0xffff0000, v199
	v_pk_mul_f32 v[64:65], v[64:65], v[240:241]
	v_pk_mul_f32 v[66:67], v[66:67], v[242:243]
	v_cvt_pk_bf16_f32 v80, v80, v81
	v_cvt_pk_bf16_f32 v81, v82, v83
	v_cvt_pk_bf16_f32 v82, v64, v65
	v_cvt_pk_bf16_f32 v83, v66, v67
	s_nop 1
	v_permlane16_swap_b32_e32 v80, v82
	v_permlane16_swap_b32_e32 v81, v83
	global_store_dwordx4 v[134:135], v[80:83], off offset:64
	s_waitcnt vmcnt(15)
	v_permlane16_swap_b32_e32 v200, v202
	v_permlane16_swap_b32_e32 v201, v203
	v_pk_mul_f32 v[88:89], v[88:89], v[152:153]
	v_pk_mul_f32 v[90:91], v[90:91], v[154:155]
	v_pk_mul_f32 v[72:73], v[72:73], v[156:157]
	v_pk_mul_f32 v[74:75], v[74:75], v[158:159]
	v_lshlrev_b32_e32 v240, 16, v200
	v_and_b32_e32 v241, 0xffff0000, v200
	v_lshlrev_b32_e32 v242, 16, v201
	v_and_b32_e32 v243, 0xffff0000, v201
	v_pk_mul_f32 v[88:89], v[88:89], v[240:241]
	v_pk_mul_f32 v[90:91], v[90:91], v[242:243]
	v_lshlrev_b32_e32 v240, 16, v202
	v_and_b32_e32 v241, 0xffff0000, v202
	v_lshlrev_b32_e32 v242, 16, v203
	v_and_b32_e32 v243, 0xffff0000, v203
	v_pk_mul_f32 v[72:73], v[72:73], v[240:241]
	v_pk_mul_f32 v[74:75], v[74:75], v[242:243]
	v_cvt_pk_bf16_f32 v88, v88, v89
	v_cvt_pk_bf16_f32 v89, v90, v91
	v_cvt_pk_bf16_f32 v90, v72, v73
	v_cvt_pk_bf16_f32 v91, v74, v75
	s_nop 1
	v_permlane16_swap_b32_e32 v88, v90
	v_permlane16_swap_b32_e32 v89, v91
	global_store_dwordx4 v[136:137], v[88:91], off offset:64
	s_waitcnt vmcnt(15)
	v_permlane16_swap_b32_e32 v204, v206
	v_permlane16_swap_b32_e32 v205, v207
	v_pk_mul_f32 v[84:85], v[84:85], v[152:153]
	v_pk_mul_f32 v[86:87], v[86:87], v[154:155]
	v_pk_mul_f32 v[68:69], v[68:69], v[156:157]
	v_pk_mul_f32 v[70:71], v[70:71], v[158:159]
	v_lshlrev_b32_e32 v240, 16, v204
	v_and_b32_e32 v241, 0xffff0000, v204
	v_lshlrev_b32_e32 v242, 16, v205
	v_and_b32_e32 v243, 0xffff0000, v205
	v_pk_mul_f32 v[84:85], v[84:85], v[240:241]
	v_pk_mul_f32 v[86:87], v[86:87], v[242:243]
	v_lshlrev_b32_e32 v240, 16, v206
	v_and_b32_e32 v241, 0xffff0000, v206
	v_lshlrev_b32_e32 v242, 16, v207
	v_and_b32_e32 v243, 0xffff0000, v207
	v_pk_mul_f32 v[68:69], v[68:69], v[240:241]
	v_pk_mul_f32 v[70:71], v[70:71], v[242:243]
	v_cvt_pk_bf16_f32 v84, v84, v85
	v_cvt_pk_bf16_f32 v85, v86, v87
	v_cvt_pk_bf16_f32 v86, v68, v69
	v_cvt_pk_bf16_f32 v87, v70, v71
	s_nop 1
	v_permlane16_swap_b32_e32 v84, v86
	v_permlane16_swap_b32_e32 v85, v87
	global_store_dwordx4 v[138:139], v[84:87], off offset:64
	s_waitcnt vmcnt(15)
	v_permlane16_swap_b32_e32 v208, v210
	v_permlane16_swap_b32_e32 v209, v211
	v_pk_mul_f32 v[60:61], v[60:61], v[160:161]
	v_pk_mul_f32 v[62:63], v[62:63], v[162:163]
	v_pk_mul_f32 v[44:45], v[44:45], v[164:165]
	v_pk_mul_f32 v[46:47], v[46:47], v[166:167]
	v_lshlrev_b32_e32 v240, 16, v208
	v_and_b32_e32 v241, 0xffff0000, v208
	v_lshlrev_b32_e32 v242, 16, v209
	v_and_b32_e32 v243, 0xffff0000, v209
	v_pk_mul_f32 v[60:61], v[60:61], v[240:241]
	v_pk_mul_f32 v[62:63], v[62:63], v[242:243]
	v_lshlrev_b32_e32 v240, 16, v210
	v_and_b32_e32 v241, 0xffff0000, v210
	v_lshlrev_b32_e32 v242, 16, v211
	v_and_b32_e32 v243, 0xffff0000, v211
	v_pk_mul_f32 v[44:45], v[44:45], v[240:241]
	v_pk_mul_f32 v[46:47], v[46:47], v[242:243]
	v_cvt_pk_bf16_f32 v60, v60, v61
	v_cvt_pk_bf16_f32 v61, v62, v63
	v_cvt_pk_bf16_f32 v62, v44, v45
	v_cvt_pk_bf16_f32 v63, v46, v47
	s_nop 1
	v_permlane16_swap_b32_e32 v60, v62
	v_permlane16_swap_b32_e32 v61, v63
	global_store_dwordx4 v[130:131], v[60:63], off offset:256
	s_waitcnt vmcnt(15)
; __device__ __forceinline__ float bf_lo(u32 v) { return __uint_as_float(v << 16); }
; __device__ __forceinline__ float bf_hi(u32 v) { return __uint_as_float(v & 0xffff0000u); }
; __device__ __forceinline__ void gemm_tile(const TileDesc& td, char* shm_c, const int wv) {
;     ...
;   } else {
;     #pragma unroll
;     for (int ai = 0; ai < 2; ++ai)
;     #pragma unroll
;     for (int m = 0; m < 4; ++m) {
;       int f0 = td.brow + ai * 128 + m * 16 + ar_l;
;       float4 ps = *(const float4*)(td.aux + f0);
;       #pragma unroll
;       for (int bj = 0; bj < 2; ++bj)
;       #pragma unroll
;       for (int n = 0; n < 2; ++n) {
;         long o = (long)(td.bcol + bj * 128 + n * 16 + br_l) * td.ldo + f0;
;         uint2 g = *(const uint2*)(td.outb + o);
;         f32x4 v = acc[ai][bj][m][n];
;         uint2 pk;
;         pk.x = pack2(v[0] * ps.x * bf_lo(g.x), v[1] * ps.y * bf_hi(g.x));
;         pk.y = pack2(v[2] * ps.z * bf_lo(g.y), v[3] * ps.w * bf_hi(g.y));
;         *(uint2*)(td.outb + o) = pk;
;       }
;     }
	v_permlane16_swap_b32_e32 v212, v214
	v_permlane16_swap_b32_e32 v213, v215
	v_pk_mul_f32 v[48:49], v[48:49], v[160:161]
	v_pk_mul_f32 v[50:51], v[50:51], v[162:163]
	v_pk_mul_f32 v[32:33], v[32:33], v[164:165]
	v_pk_mul_f32 v[34:35], v[34:35], v[166:167]
	v_lshlrev_b32_e32 v240, 16, v212
	v_and_b32_e32 v241, 0xffff0000, v212
	v_lshlrev_b32_e32 v242, 16, v213
	v_and_b32_e32 v243, 0xffff0000, v213
	v_pk_mul_f32 v[48:49], v[48:49], v[240:241]
	v_pk_mul_f32 v[50:51], v[50:51], v[242:243]
	v_lshlrev_b32_e32 v240, 16, v214
	v_and_b32_e32 v241, 0xffff0000, v214
	v_lshlrev_b32_e32 v242, 16, v215
	v_and_b32_e32 v243, 0xffff0000, v215
	v_pk_mul_f32 v[32:33], v[32:33], v[240:241]
	v_pk_mul_f32 v[34:35], v[34:35], v[242:243]
	v_cvt_pk_bf16_f32 v48, v48, v49
	v_cvt_pk_bf16_f32 v49, v50, v51
	v_cvt_pk_bf16_f32 v50, v32, v33
	v_cvt_pk_bf16_f32 v51, v34, v35
	s_nop 1
	v_permlane16_swap_b32_e32 v48, v50
	v_permlane16_swap_b32_e32 v49, v51
	global_store_dwordx4 v[134:135], v[48:51], off offset:256
	s_waitcnt vmcnt(15)
	v_permlane16_swap_b32_e32 v216, v218
	v_permlane16_swap_b32_e32 v217, v219
	v_pk_mul_f32 v[56:57], v[56:57], v[160:161]
	v_pk_mul_f32 v[58:59], v[58:59], v[162:163]
	v_pk_mul_f32 v[40:41], v[40:41], v[164:165]
	v_pk_mul_f32 v[42:43], v[42:43], v[166:167]
	v_lshlrev_b32_e32 v240, 16, v216
	v_and_b32_e32 v241, 0xffff0000, v216
	v_lshlrev_b32_e32 v242, 16, v217
	v_and_b32_e32 v243, 0xffff0000, v217
	v_pk_mul_f32 v[56:57], v[56:57], v[240:241]
	v_pk_mul_f32 v[58:59], v[58:59], v[242:243]
	v_lshlrev_b32_e32 v240, 16, v218
	v_and_b32_e32 v241, 0xffff0000, v218
	v_lshlrev_b32_e32 v242, 16, v219
	v_and_b32_e32 v243, 0xffff0000, v219
	v_pk_mul_f32 v[40:41], v[40:41], v[240:241]
	v_pk_mul_f32 v[42:43], v[42:43], v[242:243]
	v_cvt_pk_bf16_f32 v56, v56, v57
	v_cvt_pk_bf16_f32 v57, v58, v59
	v_cvt_pk_bf16_f32 v58, v40, v41
	v_cvt_pk_bf16_f32 v59, v42, v43
	s_nop 1
	v_permlane16_swap_b32_e32 v56, v58
	v_permlane16_swap_b32_e32 v57, v59
	global_store_dwordx4 v[136:137], v[56:59], off offset:256
	s_waitcnt vmcnt(15)
	v_permlane16_swap_b32_e32 v220, v222
	v_permlane16_swap_b32_e32 v221, v223
	v_pk_mul_f32 v[52:53], v[52:53], v[160:161]
	v_pk_mul_f32 v[54:55], v[54:55], v[162:163]
	v_pk_mul_f32 v[36:37], v[36:37], v[164:165]
	v_pk_mul_f32 v[38:39], v[38:39], v[166:167]
	v_lshlrev_b32_e32 v240, 16, v220
	v_and_b32_e32 v241, 0xffff0000, v220
	v_lshlrev_b32_e32 v242, 16, v221
	v_and_b32_e32 v243, 0xffff0000, v221
	v_pk_mul_f32 v[52:53], v[52:53], v[240:241]
	v_pk_mul_f32 v[54:55], v[54:55], v[242:243]
	v_lshlrev_b32_e32 v240, 16, v222
	v_and_b32_e32 v241, 0xffff0000, v222
	v_lshlrev_b32_e32 v242, 16, v223
	v_and_b32_e32 v243, 0xffff0000, v223
	v_pk_mul_f32 v[36:37], v[36:37], v[240:241]
	v_pk_mul_f32 v[38:39], v[38:39], v[242:243]
	v_cvt_pk_bf16_f32 v52, v52, v53
	v_cvt_pk_bf16_f32 v53, v54, v55
	v_cvt_pk_bf16_f32 v54, v36, v37
	v_cvt_pk_bf16_f32 v55, v38, v39
	s_nop 1
	v_permlane16_swap_b32_e32 v52, v54
	v_permlane16_swap_b32_e32 v53, v55
	global_store_dwordx4 v[138:139], v[52:55], off offset:256
	s_waitcnt vmcnt(15)
; __device__ __forceinline__ float bf_lo(u32 v) { return __uint_as_float(v << 16); }
; __device__ __forceinline__ float bf_hi(u32 v) { return __uint_as_float(v & 0xffff0000u); }
; __device__ __forceinline__ void gemm_tile(const TileDesc& td, char* shm_c, const int wv) {
;     ...
;   } else {
;     #pragma unroll
;     for (int ai = 0; ai < 2; ++ai)
;     #pragma unroll
;     for (int m = 0; m < 4; ++m) {
;       int f0 = td.brow + ai * 128 + m * 16 + ar_l;
;       float4 ps = *(const float4*)(td.aux + f0);
;       #pragma unroll
;       for (int bj = 0; bj < 2; ++bj)
;       #pragma unroll
;       for (int n = 0; n < 2; ++n) {
;         long o = (long)(td.bcol + bj * 128 + n * 16 + br_l) * td.ldo + f0;
;         uint2 g = *(const uint2*)(td.outb + o);
;         f32x4 v = acc[ai][bj][m][n];
;         uint2 pk;
;         pk.x = pack2(v[0] * ps.x * bf_lo(g.x), v[1] * ps.y * bf_hi(g.x));
;         pk.y = pack2(v[2] * ps.z * bf_lo(g.y), v[3] * ps.w * bf_hi(g.y));
;         *(uint2*)(td.outb + o) = pk;
;       }
;     }
	v_permlane16_swap_b32_e32 v224, v226
	v_permlane16_swap_b32_e32 v225, v227
	v_pk_mul_f32 v[28:29], v[28:29], v[168:169]
	v_pk_mul_f32 v[30:31], v[30:31], v[170:171]
	v_pk_mul_f32 v[12:13], v[12:13], v[172:173]
	v_pk_mul_f32 v[14:15], v[14:15], v[174:175]
	v_lshlrev_b32_e32 v240, 16, v224
	v_and_b32_e32 v241, 0xffff0000, v224
	v_lshlrev_b32_e32 v242, 16, v225
	v_and_b32_e32 v243, 0xffff0000, v225
	v_pk_mul_f32 v[28:29], v[28:29], v[240:241]
	v_pk_mul_f32 v[30:31], v[30:31], v[242:243]
	v_lshlrev_b32_e32 v240, 16, v226
	v_and_b32_e32 v241, 0xffff0000, v226
	v_lshlrev_b32_e32 v242, 16, v227
	v_and_b32_e32 v243, 0xffff0000, v227
	v_pk_mul_f32 v[12:13], v[12:13], v[240:241]
	v_pk_mul_f32 v[14:15], v[14:15], v[242:243]
	v_cvt_pk_bf16_f32 v28, v28, v29
	v_cvt_pk_bf16_f32 v29, v30, v31
	v_cvt_pk_bf16_f32 v30, v12, v13
	v_cvt_pk_bf16_f32 v31, v14, v15
	s_nop 1
	v_permlane16_swap_b32_e32 v28, v30
	v_permlane16_swap_b32_e32 v29, v31
	global_store_dwordx4 v[130:131], v[28:31], off offset:320
	s_waitcnt vmcnt(15)
	v_permlane16_swap_b32_e32 v228, v230
	v_permlane16_swap_b32_e32 v229, v231
	v_pk_mul_f32 v[16:17], v[16:17], v[168:169]
	v_pk_mul_f32 v[18:19], v[18:19], v[170:171]
	v_pk_mul_f32 v[0:1], v[0:1], v[172:173]
	v_pk_mul_f32 v[2:3], v[2:3], v[174:175]
	v_lshlrev_b32_e32 v240, 16, v228
	v_and_b32_e32 v241, 0xffff0000, v228
	v_lshlrev_b32_e32 v242, 16, v229
	v_and_b32_e32 v243, 0xffff0000, v229
	v_pk_mul_f32 v[16:17], v[16:17], v[240:241]
	v_pk_mul_f32 v[18:19], v[18:19], v[242:243]
	v_lshlrev_b32_e32 v240, 16, v230
	v_and_b32_e32 v241, 0xffff0000, v230
	v_lshlrev_b32_e32 v242, 16, v231
	v_and_b32_e32 v243, 0xffff0000, v231
	v_pk_mul_f32 v[0:1], v[0:1], v[240:241]
	v_pk_mul_f32 v[2:3], v[2:3], v[242:243]
	v_cvt_pk_bf16_f32 v16, v16, v17
	v_cvt_pk_bf16_f32 v17, v18, v19
	v_cvt_pk_bf16_f32 v18, v0, v1
	v_cvt_pk_bf16_f32 v19, v2, v3
	s_nop 1
	v_permlane16_swap_b32_e32 v16, v18
	v_permlane16_swap_b32_e32 v17, v19
	global_store_dwordx4 v[134:135], v[16:19], off offset:320
	s_waitcnt vmcnt(15)
	v_permlane16_swap_b32_e32 v232, v234
	v_permlane16_swap_b32_e32 v233, v235
	v_pk_mul_f32 v[24:25], v[24:25], v[168:169]
	v_pk_mul_f32 v[26:27], v[26:27], v[170:171]
	v_pk_mul_f32 v[4:5], v[4:5], v[172:173]
	v_pk_mul_f32 v[6:7], v[6:7], v[174:175]
	v_lshlrev_b32_e32 v240, 16, v232
	v_and_b32_e32 v241, 0xffff0000, v232
	v_lshlrev_b32_e32 v242, 16, v233
	v_and_b32_e32 v243, 0xffff0000, v233
	v_pk_mul_f32 v[24:25], v[24:25], v[240:241]
	v_pk_mul_f32 v[26:27], v[26:27], v[242:243]
	v_lshlrev_b32_e32 v240, 16, v234
	v_and_b32_e32 v241, 0xffff0000, v234
	v_lshlrev_b32_e32 v242, 16, v235
	v_and_b32_e32 v243, 0xffff0000, v235
	v_pk_mul_f32 v[4:5], v[4:5], v[240:241]
	v_pk_mul_f32 v[6:7], v[6:7], v[242:243]
	v_cvt_pk_bf16_f32 v24, v24, v25
	v_cvt_pk_bf16_f32 v25, v26, v27
	v_cvt_pk_bf16_f32 v26, v4, v5
	v_cvt_pk_bf16_f32 v27, v6, v7
	s_nop 1
	v_permlane16_swap_b32_e32 v24, v26
	v_permlane16_swap_b32_e32 v25, v27
	global_store_dwordx4 v[136:137], v[24:27], off offset:320
	s_waitcnt vmcnt(15)
	v_permlane16_swap_b32_e32 v236, v238
	v_permlane16_swap_b32_e32 v237, v239
	v_pk_mul_f32 v[20:21], v[20:21], v[168:169]
	v_pk_mul_f32 v[22:23], v[22:23], v[170:171]
	v_pk_mul_f32 v[8:9], v[8:9], v[172:173]
	v_pk_mul_f32 v[10:11], v[10:11], v[174:175]
	v_lshlrev_b32_e32 v240, 16, v236
	v_and_b32_e32 v241, 0xffff0000, v236
	v_lshlrev_b32_e32 v242, 16, v237
	v_and_b32_e32 v243, 0xffff0000, v237
	v_pk_mul_f32 v[20:21], v[20:21], v[240:241]
	v_pk_mul_f32 v[22:23], v[22:23], v[242:243]
	v_lshlrev_b32_e32 v240, 16, v238
	v_and_b32_e32 v241, 0xffff0000, v238
	v_lshlrev_b32_e32 v242, 16, v239
	v_and_b32_e32 v243, 0xffff0000, v239
	v_pk_mul_f32 v[8:9], v[8:9], v[240:241]
	v_pk_mul_f32 v[10:11], v[10:11], v[242:243]
	v_cvt_pk_bf16_f32 v20, v20, v21
	v_cvt_pk_bf16_f32 v21, v22, v23
	v_cvt_pk_bf16_f32 v22, v8, v9
	v_cvt_pk_bf16_f32 v23, v10, v11
	s_nop 1
	v_permlane16_swap_b32_e32 v20, v22
	v_permlane16_swap_b32_e32 v21, v23
	global_store_dwordx4 v[138:139], v[20:23], off offset:320
	s_cbranch_scc0 .LBB0_489
